# baseline (speedup 1.0000x reference)
; #define QK_FENCE() __builtin_amdgcn_sched_barrier(0x406)
; DI void partialSM(f32x16& p0, f32x16& p1, float& m_reg, float& mn, float& alpha) {
;     ...
;   else { mn = fmaxf(m_reg, pmax); alpha = __builtin_amdgcn_exp2f((m_reg - mn) * C); m_reg = mn; }
;   const float mnC = -mn * C;
; #pragma unroll
;   for (int r = 0; r < 16; ++r) p0[r] = fmaf(p0[r], C, mnC);
; #pragma unroll
;   for (int r = 0; r < 16; ++r) p1[r] = fmaf(p1[r], C, mnC);
; #pragma unroll
;   for (int r = 0; r < 16; ++r) p0[r] = __builtin_amdgcn_exp2f(p0[r]);
; }
; DI void finishSM(f32x16& p0, f32x16& p1, float alpha, float& l_reg, bf16x8& pa0, bf16x8& pa1, bf16x8& pa2, bf16x8& pa3) {
; #pragma unroll
;   for (int r = 0; r < 16; ++r) p1[r] = __builtin_amdgcn_exp2f(p1[r]);
;   float ps = 0;
; #pragma unroll
;   for (int r = 0; r < 16; ++r) ps += p0[r];
; #pragma unroll
;   for (int r = 0; r < 16; ++r) ps += p1[r];
;   { auto rr = __builtin_amdgcn_permlane32_swap(__float_as_uint(ps), __float_as_uint(ps), false, false);
;     ps = __uint_as_float(rr[0]) + __uint_as_float(rr[1]); }
;   l_reg = l_reg * alpha + ps;
; DI void qkt12(f32x16& p0, f32x16& p1, const char* Kt, const char* Rt, const int* ko, const int* ro, const bf16x8* qr) {
;   { const f32x16 z = {0.f, 0.f, 0.f, 0.f, 0.f, 0.f, 0.f, 0.f, 0.f, 0.f, 0.f, 0.f, 0.f, 0.f, 0.f, 0.f}; p0 = z; p1 = z; }
;   const char* kp[4] = {Kt + ko[0], Kt + ko[1], Kt + ko[2], Kt + ko[3]};
;   const char* rp[4] = {Rt + ro[0], Rt + ro[1], Rt + ro[2], Rt + ro[3]};
;   bf16x8 ka[2], kb[2];
;   ka[0] = *reinterpret_cast<const bf16x8*>(kp[0]); kb[0] = *reinterpret_cast<const bf16x8*>(kp[0] + 8192);
; #pragma unroll
;   for (int d0 = 0; d0 < 12; ++d0) {
;     if (d0 + 1 < 12) { const int d1 = d0 + 1;
;       if (d1 < 8) { ka[d1 & 1] = *reinterpret_cast<const bf16x8*>(kp[d1 & 3] + (d1 >> 2) * 128); kb[d1 & 1] = *reinterpret_cast<const bf16x8*>(kp[d1 & 3] + (d1 >> 2) * 128 + 8192); }
;       else { ka[d1 & 1] = *reinterpret_cast<const bf16x8*>(rp[d1 - 8]); kb[d1 & 1] = *reinterpret_cast<const bf16x8*>(rp[d1 - 8] + 4096); } }
;     QK_FENCE();
;     p0 = __builtin_amdgcn_mfma_f32_32x32x16_bf16(ka[d0 & 1], qr[d0], p0, 0, 0, 0);
;     p1 = __builtin_amdgcn_mfma_f32_32x32x16_bf16(kb[d0 & 1], qr[d0], p1, 0, 0, 0);
;     QK_FENCE();
;   }
.LBB0_128:
	s_add_i32 s2, s12, -1
	s_cmp_ge_u32 s2, s52
	s_cbranch_scc1 .Lattn_bb2_nodma
	v_cndmask_b32_e64 v160, v160, v187, s[38:39]
	s_add_i32 s2, s42, 0xa000
	s_cmp_lg_u32 s61, 2
	s_cselect_b32 s2, s2, 0
	s_add_i32 s6, s2, 16
	v_add_u32_e32 v213, s6, v176
	ds_read_b128 v[222:225], v213 offset:16384
	v_add_u32_e32 v230, s6, v179
	ds_read_b128 v[226:229], v213 offset:24576
	ds_read_b128 v[214:217], v230 offset:16384
	ds_read_b128 v[218:221], v230 offset:24576
	v_add_u32_e32 v231, s6, v180
	v_add_u32_e32 v234, s6, v181
	v_mul_f32_e32 v197, 0xbdd53b94, v160
	v_fmamk_f32 v161, v94, 0x3dd53b94, v197
	v_fmamk_f32 v194, v80, 0x3dd53b94, v197
	v_fmamk_f32 v196, v81, 0x3dd53b94, v197
	v_fmamk_f32 v192, v82, 0x3dd53b94, v197
	v_fmamk_f32 v195, v83, 0x3dd53b94, v197
	v_fmamk_f32 v187, v84, 0x3dd53b94, v197
	v_fmamk_f32 v193, v85, 0x3dd53b94, v197
	v_fmamk_f32 v169, v86, 0x3dd53b94, v197
	v_fmamk_f32 v190, v87, 0x3dd53b94, v197
	v_fmamk_f32 v166, v88, 0x3dd53b94, v197
	v_fmamk_f32 v168, v89, 0x3dd53b94, v197
	v_fmamk_f32 v164, v90, 0x3dd53b94, v197
	s_waitcnt lgkmcnt(3)
	v_fmamk_f32 v167, v91, 0x3dd53b94, v197
	v_fmamk_f32 v162, v92, 0x3dd53b94, v197
	v_fmamk_f32 v165, v93, 0x3dd53b94, v197
	v_fmamk_f32 v163, v95, 0x3dd53b94, v197
	v_mfma_f32_32x32x16_bf16 v[80:95], v[222:225], v[134:137], 0
	v_fmamk_f32 v208, v74, 0x3dd53b94, v197
	v_fmamk_f32 v209, v75, 0x3dd53b94, v197
	v_fmamk_f32 v198, v64, 0x3dd53b94, v197
	v_fmamk_f32 v199, v65, 0x3dd53b94, v197
	v_fmamk_f32 v200, v66, 0x3dd53b94, v197
	v_fmamk_f32 v201, v67, 0x3dd53b94, v197
	v_fmamk_f32 v202, v68, 0x3dd53b94, v197
	s_waitcnt lgkmcnt(1)
	v_mfma_f32_32x32x16_bf16 v[80:95], v[214:217], v[130:133], v[80:95]
	v_fmamk_f32 v203, v69, 0x3dd53b94, v197
	v_fmamk_f32 v204, v70, 0x3dd53b94, v197
	v_fmamk_f32 v205, v71, 0x3dd53b94, v197
	v_fmamk_f32 v206, v72, 0x3dd53b94, v197
	v_fmamk_f32 v207, v73, 0x3dd53b94, v197
	v_fmamk_f32 v210, v76, 0x3dd53b94, v197
	v_fmamk_f32 v211, v77, 0x3dd53b94, v197
	v_fmamk_f32 v212, v78, 0x3dd53b94, v197
	v_fmac_f32_e32 v197, 0x3dd53b94, v79
	v_mfma_f32_32x32x16_bf16 v[64:79], v[226:229], v[134:137], 0
	v_add_u32_e32 v240, s44, v178
	v_exp_f32_e32 v161, v161
	v_readfirstlane_b32 s2, v240
	s_mov_b64 s[0:1], 0x1bc00100
	v_lshl_add_u64 v[238:239], v[158:159], 0, s[0:1]
	s_mov_b32 m0, s2
	v_exp_f32_e32 v194, v194
	global_load_lds_dwordx4 v[238:239], off
	ds_read_b128 v[222:225], v231 offset:16384
	ds_read_b128 v[226:229], v231 offset:24576
	s_waitcnt lgkmcnt(2)
	v_mfma_f32_32x32x16_bf16 v[64:79], v[218:221], v[130:133], v[64:79]
	ds_read_b128 v[214:217], v234 offset:16384
	ds_read_b128 v[218:221], v234 offset:24576
	v_exp_f32_e32 v196, v196
	v_exp_f32_e32 v192, v192
	v_exp_f32_e32 v195, v195
	s_waitcnt lgkmcnt(3)
	v_mfma_f32_32x32x16_bf16 v[80:95], v[222:225], v[126:129], v[80:95]
	v_exp_f32_e32 v187, v187
	v_exp_f32_e32 v193, v193
	v_exp_f32_e32 v169, v169
	s_waitcnt lgkmcnt(2)
	v_mfma_f32_32x32x16_bf16 v[64:79], v[226:229], v[126:129], v[64:79]
	ds_read_b128 v[222:225], v213 offset:16512
	ds_read_b128 v[226:229], v213 offset:24704
	v_add_u32_e32 v213, s6, v182
	v_exp_f32_e32 v190, v190
	v_exp_f32_e32 v166, v166
	v_exp_f32_e32 v168, v168
	s_waitcnt lgkmcnt(3)
	v_mfma_f32_32x32x16_bf16 v[80:95], v[214:217], v[114:117], v[80:95]
	v_add_u32_e32 v242, 0x2000, v240
	s_mov_b64 s[0:1], 0x1bc20100
	v_lshl_add_u64 v[238:239], v[158:159], 0, s[0:1]
	v_readfirstlane_b32 s2, v242
	s_mov_b32 m0, s2
	v_exp_f32_e32 v164, v164
	global_load_lds_dwordx4 v[238:239], off
	v_exp_f32_e32 v167, v167
	s_waitcnt lgkmcnt(2)
	v_mfma_f32_32x32x16_bf16 v[64:79], v[218:221], v[114:117], v[64:79]
	ds_read_b128 v[214:217], v230 offset:16512
	ds_read_b128 v[218:221], v230 offset:24704
	v_exp_f32_e32 v162, v162
	v_exp_f32_e32 v165, v165
	v_exp_f32_e32 v163, v163
	s_waitcnt lgkmcnt(3)
	v_mfma_f32_32x32x16_bf16 v[80:95], v[222:225], v[110:113], v[80:95]
	v_exp_f32_e32 v198, v198
	v_exp_f32_e32 v199, v199
	v_exp_f32_e32 v200, v200
	s_waitcnt lgkmcnt(2)
	v_mfma_f32_32x32x16_bf16 v[64:79], v[226:229], v[110:113], v[64:79]
	ds_read_b128 v[222:225], v231 offset:16512
	ds_read_b128 v[226:229], v231 offset:24704
	v_exp_f32_e32 v201, v201
	v_exp_f32_e32 v202, v202
	v_exp_f32_e32 v203, v203
	s_waitcnt lgkmcnt(3)
	v_mfma_f32_32x32x16_bf16 v[80:95], v[214:217], v[106:109], v[80:95]
	v_add_u32_e32 v242, 0x4000, v240
	s_mov_b64 s[0:1], 0x1bc00000
	v_lshl_add_u64 v[238:239], v[156:157], 0, s[0:1]
	v_readfirstlane_b32 s2, v242
	s_mov_b32 m0, s2
	v_exp_f32_e32 v204, v204
	global_load_lds_dwordx4 v[238:239], off
	v_exp_f32_e32 v205, v205
	s_waitcnt lgkmcnt(2)
	v_mfma_f32_32x32x16_bf16 v[64:79], v[218:221], v[106:109], v[64:79]
	ds_read_b128 v[214:217], v234 offset:16512
	ds_read_b128 v[218:221], v234 offset:24704
	v_exp_f32_e32 v206, v206
	v_exp_f32_e32 v207, v207
	v_exp_f32_e32 v210, v210
	s_waitcnt lgkmcnt(3)
	v_mfma_f32_32x32x16_bf16 v[80:95], v[222:225], v[102:105], v[80:95]
	v_exp_f32_e32 v211, v211
	v_exp_f32_e32 v212, v212
	v_exp_f32_e32 v235, v208
	s_waitcnt lgkmcnt(2)
	v_mfma_f32_32x32x16_bf16 v[64:79], v[226:229], v[102:105], v[64:79]
	ds_read_b128 v[222:225], v213 offset:32768
	ds_read_b128 v[226:229], v213 offset:36864
	v_add_u32_e32 v213, s6, v183
	v_exp_f32_e32 v237, v197
	v_add_f32_e32 v197, 0, v194
	v_add_f32_e32 v197, v196, v197
	v_add_f32_e32 v197, v192, v197
	v_add_f32_e32 v197, v195, v197
	s_waitcnt lgkmcnt(3)
	v_mfma_f32_32x32x16_bf16 v[80:95], v[214:217], v[98:101], v[80:95]
	v_add_u32_e32 v242, 0x6000, v240
	s_mov_b64 s[0:1], 0x1bc20000
	v_lshl_add_u64 v[238:239], v[156:157], 0, s[0:1]
	v_readfirstlane_b32 s2, v242
	s_mov_b32 m0, s2
	v_add_f32_e32 v197, v187, v197
	global_load_lds_dwordx4 v[238:239], off
	v_add_f32_e32 v197, v193, v197
	v_add_f32_e32 v197, v169, v197
	v_add_f32_e32 v197, v190, v197
	s_waitcnt lgkmcnt(2)
; #define SBAR() __builtin_amdgcn_sched_barrier(0)
; template <int OFF> DI s16x4 tr_read(int vb) { s16x4 r; asm volatile("ds_read_b64_tr_b16 %0, %1 offset:%2" : "=&v"(r) : "v"(vb), "i"(OFF) : "memory"); return r; }
; DI void finishSM(f32x16& p0, f32x16& p1, float alpha, float& l_reg, bf16x8& pa0, bf16x8& pa1, bf16x8& pa2, bf16x8& pa3) {
; #pragma unroll
;   for (int r = 0; r < 16; ++r) p1[r] = __builtin_amdgcn_exp2f(p1[r]);
;   float ps = 0;
; #pragma unroll
;   for (int r = 0; r < 16; ++r) ps += p0[r];
; #pragma unroll
;   for (int r = 0; r < 16; ++r) ps += p1[r];
;   { auto rr = __builtin_amdgcn_permlane32_swap(__float_as_uint(ps), __float_as_uint(ps), false, false);
;     ps = __uint_as_float(rr[0]) + __uint_as_float(rr[1]); }
;   l_reg = l_reg * alpha + ps;
;     ...
;   PK4(p0, 0, pa0); PK4(p0, 8, pa1); PK4(p1, 0, pa2); PK4(p1, 8, pa3);
; template <int D0> DI void pv_one(f32x16& od, int vb, bf16x8 pa0, bf16x8 pa1, bf16x8 pa2, bf16x8 pa3) {
;   const s16x4 l0 = tr_read<v_rd_off(D0, 0, 0)>(vb), h0 = tr_read<v_rd_off(D0, 0, 1)>(vb), l1 = tr_read<v_rd_off(D0, 1, 0)>(vb), h1 = tr_read<v_rd_off(D0, 1, 1)>(vb);
;   const s16x4 l2 = tr_read<v_rd_off(D0, 2, 0)>(vb), h2 = tr_read<v_rd_off(D0, 2, 1)>(vb), l3 = tr_read<v_rd_off(D0, 3, 0)>(vb), h3 = tr_read<v_rd_off(D0, 3, 1)>(vb);
;   asm volatile("s_waitcnt lgkmcnt(0)" ::: "memory"); SBAR();
;     ...
;   od = __builtin_amdgcn_mfma_f32_32x32x16_bf16(pa0, PK(l0, h0), od, 0, 0, 0);
;   od = __builtin_amdgcn_mfma_f32_32x32x16_bf16(pa1, PK(l1, h1), od, 0, 0, 0);
;   od = __builtin_amdgcn_mfma_f32_32x32x16_bf16(pa2, PK(l2, h2), od, 0, 0, 0);
;   od = __builtin_amdgcn_mfma_f32_32x32x16_bf16(pa3, PK(l3, h3), od, 0, 0, 0);
;     ...
; }
; DI void pv_d0(f32x16* o, int vb, bf16x8 pa0, bf16x8 pa1, bf16x8 pa2, bf16x8 pa3) {
;   pv_one<0>(o[0], vb, pa0, pa1, pa2, pa3); pv_one<1>(o[1], vb, pa0, pa1, pa2, pa3); pv_one<2>(o[2], vb, pa0, pa1, pa2, pa3); pv_one<3>(o[3], vb, pa0, pa1, pa2, pa3);
	v_mfma_f32_32x32x16_bf16 v[64:79], v[218:221], v[98:101], v[64:79]
	ds_read_b128 v[214:217], v213 offset:32768
	ds_read_b128 v[218:221], v213 offset:36864
	v_add_u32_e32 v213, s6, v184
	v_add_f32_e32 v197, v166, v197
	v_add_f32_e32 v197, v168, v197
	v_add_f32_e32 v197, v164, v197
	v_add_f32_e32 v197, v167, v197
	v_add_f32_e32 v197, v162, v197
	v_add_f32_e32 v197, v165, v197
	s_waitcnt lgkmcnt(3)
	v_mfma_f32_32x32x16_bf16 v[80:95], v[222:225], v[122:125], v[80:95]
	v_add_f32_e32 v197, v161, v197
	v_add_f32_e32 v197, v163, v197
	v_add_f32_e32 v197, v198, v197
	v_add_f32_e32 v197, v199, v197
	v_add_f32_e32 v197, v200, v197
	v_add_f32_e32 v197, v201, v197
	v_add_f32_e32 v197, v202, v197
	s_waitcnt lgkmcnt(2)
	v_mfma_f32_32x32x16_bf16 v[64:79], v[226:229], v[122:125], v[64:79]
	ds_read_b128 v[222:225], v213 offset:32768
	ds_read_b128 v[226:229], v213 offset:36864
	v_add_u32_e32 v213, s6, v185
	v_add_f32_e32 v197, v203, v197
	v_add_f32_e32 v197, v204, v197
	v_exp_f32_e32 v241, v209
	v_add_f32_e32 v197, v205, v197
	v_add_f32_e32 v197, v206, v197
	s_waitcnt lgkmcnt(3)
	v_mfma_f32_32x32x16_bf16 v[80:95], v[214:217], v[142:145], v[80:95]
	v_add_u32_e32 v242, 0x8000, v240
	s_mov_b64 s[0:1], 0x1fb46000
	v_lshl_add_u64 v[238:239], v[154:155], 0, s[0:1]
	v_readfirstlane_b32 s2, v242
	s_mov_b32 m0, s2
	v_add_f32_e32 v197, v207, v197
	global_load_lds_dwordx4 v[238:239], off
	s_movk_i32 s0, 0x410
	s_movk_i32 s1, 0x1800
	v_add_f32_e32 v197, v235, v197
	v_add_f32_e32 v197, v241, v197
	v_add_f32_e32 v197, v210, v197
	s_waitcnt lgkmcnt(2)
	v_mfma_f32_32x32x16_bf16 v[64:79], v[218:221], v[142:145], v[64:79]
	ds_read_b128 v[214:217], v213 offset:32768
	ds_read_b128 v[218:221], v213 offset:36864
	v_add_f32_e32 v197, v211, v197
	v_add_f32_e32 v197, v212, v197
	v_add_f32_e32 v208, v237, v197
	v_mov_b32_e32 v209, v208
	v_cvt_pk_bf16_f32 v194, v194, v196
	v_cvt_pk_bf16_f32 v195, v192, v195
	v_permlane32_swap_b32_e32 v208, v209
	s_waitcnt lgkmcnt(3)
	v_mfma_f32_32x32x16_bf16 v[80:95], v[222:225], v[118:121], v[80:95]
	v_cvt_pk_bf16_f32 v196, v187, v193
	v_cvt_pk_bf16_f32 v197, v169, v190
	v_cvt_pk_bf16_f32 v166, v166, v168
	v_cvt_pk_bf16_f32 v167, v164, v167
	v_cvt_pk_bf16_f32 v168, v162, v165
	v_cvt_pk_bf16_f32 v169, v161, v163
	v_cvt_pk_bf16_f32 v162, v198, v199
	s_waitcnt lgkmcnt(2)
	v_mfma_f32_32x32x16_bf16 v[64:79], v[226:229], v[118:121], v[64:79]
	v_cvt_pk_bf16_f32 v163, v200, v201
	v_cvt_pk_bf16_f32 v164, v202, v203
	v_cvt_pk_bf16_f32 v165, v204, v205
	v_cvt_pk_bf16_f32 v198, v206, v207
	v_cvt_pk_bf16_f32 v199, v235, v241
	v_cvt_pk_bf16_f32 v200, v210, v211
	v_cvt_pk_bf16_f32 v201, v212, v237
	s_waitcnt lgkmcnt(1)
	v_mfma_f32_32x32x16_bf16 v[80:95], v[214:217], v[138:141], v[80:95]
	v_permlane32_swap_b32_e32 v194, v196
	v_permlane32_swap_b32_e32 v195, v197
	v_permlane32_swap_b32_e32 v166, v168
	v_permlane32_swap_b32_e32 v167, v169
	v_permlane32_swap_b32_e32 v162, v164
	v_permlane32_swap_b32_e32 v163, v165
	v_permlane32_swap_b32_e32 v198, v200
	s_waitcnt lgkmcnt(0)
	v_mfma_f32_32x32x16_bf16 v[64:79], v[218:221], v[138:141], v[64:79]
	v_add_u32_e32 v161, s42, v174
	ds_read_b64_tr_b16 v[202:203], v161 offset:0
	ds_read_b64_tr_b16 v[204:205], v161 offset:0x800
	ds_read_b64_tr_b16 v[210:211], v161 offset:0x1000
	ds_read_b64_tr_b16 v[212:213], v161 offset:0x1800
	ds_read_b64_tr_b16 v[214:215], v161 offset:0x2000
	ds_read_b64_tr_b16 v[216:217], v161 offset:0x2800
	ds_read_b64_tr_b16 v[218:219], v161 offset:0x3000
	ds_read_b64_tr_b16 v[220:221], v161 offset:0x3800
	v_permlane32_swap_b32_e32 v199, v201
	v_max_f32_e32 v235, v81, v81
	v_max_f32_e32 v237, v80, v80
	v_max_f32_e32 v235, v237, v235
	v_max3_f32 v235, v235, v82, v83
	v_max3_f32 v235, v235, v84, v85
	s_waitcnt lgkmcnt(6)
	v_mfma_f32_32x32x16_bf16 v[0:15], v[194:197], v[202:205], v[0:15]
	ds_read_b64_tr_b16 v[202:203], v161 offset:0x200
	ds_read_b64_tr_b16 v[204:205], v161 offset:0xa00
	v_max3_f32 v235, v235, v86, v87
	v_max3_f32 v235, v235, v88, v89
	v_max3_f32 v235, v235, v90, v91
	v_max3_f32 v235, v235, v92, v93
	v_max3_f32 v235, v235, v94, v95
	v_max3_f32 v235, v235, v64, v65
	v_max3_f32 v235, v235, v66, v67
	s_waitcnt lgkmcnt(6)
	v_mfma_f32_32x32x16_bf16 v[0:15], v[166:169], v[210:213], v[0:15]
	ds_read_b64_tr_b16 v[210:211], v161 offset:0x1200
	ds_read_b64_tr_b16 v[212:213], v161 offset:0x1a00
	v_max3_f32 v235, v235, v68, v69
	v_max3_f32 v235, v235, v70, v71
	v_max3_f32 v235, v235, v72, v73
	v_max3_f32 v235, v235, v74, v75
	v_max3_f32 v235, v235, v76, v77
	v_max3_f32 v235, v235, v78, v79
	v_mov_b32_e32 v237, v235
	s_waitcnt lgkmcnt(6)
	v_mfma_f32_32x32x16_bf16 v[0:15], v[162:165], v[214:217], v[0:15]
	ds_read_b64_tr_b16 v[214:215], v161 offset:0x2200
	ds_read_b64_tr_b16 v[216:217], v161 offset:0x2a00
	v_permlane32_swap_b32_e32 v235, v237
	v_max_f32_e32 v237, v237, v237
	v_max_f32_e32 v235, v235, v235
	s_waitcnt lgkmcnt(6)
	v_mfma_f32_32x32x16_bf16 v[0:15], v[198:201], v[218:221], v[0:15]
	ds_read_b64_tr_b16 v[218:219], v161 offset:0x3200
	ds_read_b64_tr_b16 v[220:221], v161 offset:0x3a00
	s_waitcnt lgkmcnt(6)
	v_mfma_f32_32x32x16_bf16 v[48:63], v[194:197], v[202:205], v[48:63]
	ds_read_b64_tr_b16 v[202:203], v161 offset:0x400
	ds_read_b64_tr_b16 v[204:205], v161 offset:0xc00
	s_waitcnt lgkmcnt(6)
	v_mfma_f32_32x32x16_bf16 v[48:63], v[166:169], v[210:213], v[48:63]
	ds_read_b64_tr_b16 v[210:211], v161 offset:0x1400
	ds_read_b64_tr_b16 v[212:213], v161 offset:0x1c00
	s_waitcnt lgkmcnt(6)
	v_mfma_f32_32x32x16_bf16 v[48:63], v[162:165], v[214:217], v[48:63]
	ds_read_b64_tr_b16 v[214:215], v161 offset:0x2400
	ds_read_b64_tr_b16 v[216:217], v161 offset:0x2c00
	s_waitcnt lgkmcnt(6)
; #define SBAR() __builtin_amdgcn_sched_barrier(0)
; DI void partialSM(f32x16& p0, f32x16& p1, float& m_reg, float& mn, float& alpha) {
;   constexpr float C = ATT_SCALE * 1.4426950408889634f;
;   float pmax = p0[0];
; #pragma unroll
;   for (int r = 1; r < 16; ++r) pmax = fmaxf(pmax, p0[r]);
; #pragma unroll
;   for (int r = 0; r < 16; ++r) pmax = fmaxf(pmax, p1[r]);
;   { auto rr = __builtin_amdgcn_permlane32_swap(__float_as_uint(pmax), __float_as_uint(pmax), false, false);
;     pmax = fmaxf(__uint_as_float(rr[0]), __uint_as_float(rr[1])); }
;   if (__builtin_expect(__all(pmax - m_reg <= ATT_THR / ATT_SCALE), 1)) { mn = m_reg; alpha = 1.f; }
;   else { mn = fmaxf(m_reg, pmax); alpha = __builtin_amdgcn_exp2f((m_reg - mn) * C); m_reg = mn; }
;   const float mnC = -mn * C;
; #pragma unroll
;   for (int r = 0; r < 16; ++r) p0[r] = fmaf(p0[r], C, mnC);
; #pragma unroll
;   for (int r = 0; r < 16; ++r) p1[r] = fmaf(p1[r], C, mnC);
; #pragma unroll
;   for (int r = 0; r < 16; ++r) p0[r] = __builtin_amdgcn_exp2f(p0[r]);
; }
; DI void finishSM(f32x16& p0, f32x16& p1, float alpha, float& l_reg, bf16x8& pa0, bf16x8& pa1, bf16x8& pa2, bf16x8& pa3) {
; #pragma unroll
;   for (int r = 0; r < 16; ++r) p1[r] = __builtin_amdgcn_exp2f(p1[r]);
; template <int D0> DI void pv_one(f32x16& od, int vb, bf16x8 pa0, bf16x8 pa1, bf16x8 pa2, bf16x8 pa3) {
;   const s16x4 l0 = tr_read<v_rd_off(D0, 0, 0)>(vb), h0 = tr_read<v_rd_off(D0, 0, 1)>(vb), l1 = tr_read<v_rd_off(D0, 1, 0)>(vb), h1 = tr_read<v_rd_off(D0, 1, 1)>(vb);
;   const s16x4 l2 = tr_read<v_rd_off(D0, 2, 0)>(vb), h2 = tr_read<v_rd_off(D0, 2, 1)>(vb), l3 = tr_read<v_rd_off(D0, 3, 0)>(vb), h3 = tr_read<v_rd_off(D0, 3, 1)>(vb);
;   asm volatile("s_waitcnt lgkmcnt(0)" ::: "memory"); SBAR();
;     ...
;   od = __builtin_amdgcn_mfma_f32_32x32x16_bf16(pa0, PK(l0, h0), od, 0, 0, 0);
;   od = __builtin_amdgcn_mfma_f32_32x32x16_bf16(pa1, PK(l1, h1), od, 0, 0, 0);
;   od = __builtin_amdgcn_mfma_f32_32x32x16_bf16(pa2, PK(l2, h2), od, 0, 0, 0);
;   od = __builtin_amdgcn_mfma_f32_32x32x16_bf16(pa3, PK(l3, h3), od, 0, 0, 0);
;     ...
; }
; DI void pv_d0(f32x16* o, int vb, bf16x8 pa0, bf16x8 pa1, bf16x8 pa2, bf16x8 pa3) {
;   pv_one<0>(o[0], vb, pa0, pa1, pa2, pa3); pv_one<1>(o[1], vb, pa0, pa1, pa2, pa3); pv_one<2>(o[2], vb, pa0, pa1, pa2, pa3); pv_one<3>(o[3], vb, pa0, pa1, pa2, pa3);
	v_mfma_f32_32x32x16_bf16 v[48:63], v[198:201], v[218:221], v[48:63]
	ds_read_b64_tr_b16 v[218:219], v161 offset:0x3400
	ds_read_b64_tr_b16 v[220:221], v161 offset:0x3c00
	s_waitcnt lgkmcnt(6)
	v_mfma_f32_32x32x16_bf16 v[32:47], v[194:197], v[202:205], v[32:47]
	ds_read_b64_tr_b16 v[202:203], v161 offset:0x600
	ds_read_b64_tr_b16 v[204:205], v161 offset:0xe00
	s_waitcnt lgkmcnt(6)
	v_mfma_f32_32x32x16_bf16 v[32:47], v[166:169], v[210:213], v[32:47]
	ds_read_b64_tr_b16 v[210:211], v161 offset:0x1600
	ds_read_b64_tr_b16 v[212:213], v161 offset:0x1e00
	s_waitcnt lgkmcnt(6)
	v_mfma_f32_32x32x16_bf16 v[32:47], v[162:165], v[214:217], v[32:47]
	ds_read_b64_tr_b16 v[214:215], v161 offset:0x2600
	ds_read_b64_tr_b16 v[216:217], v161 offset:0x2e00
	s_waitcnt lgkmcnt(6)
	v_mfma_f32_32x32x16_bf16 v[32:47], v[198:201], v[218:221], v[32:47]
	ds_read_b64_tr_b16 v[218:219], v161 offset:0x3600
	ds_read_b64_tr_b16 v[220:221], v161 offset:0x3e00
	v_max_f32_e32 v161, v235, v237
	v_sub_f32_e32 v237, v161, v160
	s_waitcnt lgkmcnt(6)
	v_mfma_f32_32x32x16_bf16 v[16:31], v[194:197], v[202:205], v[16:31]
	s_waitcnt lgkmcnt(4)
	v_mfma_f32_32x32x16_bf16 v[16:31], v[166:169], v[210:213], v[16:31]
	s_waitcnt lgkmcnt(2)
	v_mfma_f32_32x32x16_bf16 v[16:31], v[162:165], v[214:217], v[16:31]
	s_waitcnt lgkmcnt(0)
	v_mfma_f32_32x32x16_bf16 v[16:31], v[198:201], v[218:221], v[16:31]
	v_cmp_ge_f32_e32 vcc, s65, v237
	s_cmp_eq_u64 vcc, exec
	s_cselect_b64 s[38:39], -1, 0
	s_cmp_ge_u32 s12, s52
	s_cselect_b64 s[42:43], -1, 0
	s_and_b64 vcc, exec, s[42:43]
	s_waitcnt vmcnt(0)
	s_waitcnt vmcnt(0)
	s_barrier
	s_branch .Lattn_bb2_join
.Lattn_bb2_nodma:
	v_cndmask_b32_e64 v160, v160, v187, s[38:39]
	s_add_i32 s2, s42, 0xa000
	s_cmp_lg_u32 s61, 2
	s_cselect_b32 s2, s2, 0
	s_add_i32 s6, s2, 16
	v_add_u32_e32 v213, s6, v176
	ds_read_b128 v[222:225], v213 offset:16384
	v_add_u32_e32 v230, s6, v179
	ds_read_b128 v[226:229], v213 offset:24576
	ds_read_b128 v[214:217], v230 offset:16384
	ds_read_b128 v[218:221], v230 offset:24576
	v_add_u32_e32 v231, s6, v180
	v_add_u32_e32 v234, s6, v181
	v_mul_f32_e32 v197, 0xbdd53b94, v160
	v_fmamk_f32 v161, v94, 0x3dd53b94, v197
	v_fmamk_f32 v194, v80, 0x3dd53b94, v197
	v_fmamk_f32 v196, v81, 0x3dd53b94, v197
	v_fmamk_f32 v192, v82, 0x3dd53b94, v197
	v_fmamk_f32 v195, v83, 0x3dd53b94, v197
	v_fmamk_f32 v187, v84, 0x3dd53b94, v197
	v_fmamk_f32 v193, v85, 0x3dd53b94, v197
	v_fmamk_f32 v169, v86, 0x3dd53b94, v197
	v_fmamk_f32 v190, v87, 0x3dd53b94, v197
	v_fmamk_f32 v166, v88, 0x3dd53b94, v197
	v_fmamk_f32 v168, v89, 0x3dd53b94, v197
	v_fmamk_f32 v164, v90, 0x3dd53b94, v197
	s_waitcnt lgkmcnt(3)
	v_fmamk_f32 v167, v91, 0x3dd53b94, v197
	v_fmamk_f32 v162, v92, 0x3dd53b94, v197
	v_fmamk_f32 v165, v93, 0x3dd53b94, v197
	v_fmamk_f32 v163, v95, 0x3dd53b94, v197
	v_mfma_f32_32x32x16_bf16 v[80:95], v[222:225], v[134:137], 0
	v_fmamk_f32 v208, v74, 0x3dd53b94, v197
	v_fmamk_f32 v209, v75, 0x3dd53b94, v197
	v_fmamk_f32 v198, v64, 0x3dd53b94, v197
	v_fmamk_f32 v199, v65, 0x3dd53b94, v197
	v_fmamk_f32 v200, v66, 0x3dd53b94, v197
	v_fmamk_f32 v201, v67, 0x3dd53b94, v197
	v_fmamk_f32 v202, v68, 0x3dd53b94, v197
	s_waitcnt lgkmcnt(1)
	v_mfma_f32_32x32x16_bf16 v[80:95], v[214:217], v[130:133], v[80:95]
	v_fmamk_f32 v203, v69, 0x3dd53b94, v197
	v_fmamk_f32 v204, v70, 0x3dd53b94, v197
	v_fmamk_f32 v205, v71, 0x3dd53b94, v197
	v_fmamk_f32 v206, v72, 0x3dd53b94, v197
	v_fmamk_f32 v207, v73, 0x3dd53b94, v197
	v_fmamk_f32 v210, v76, 0x3dd53b94, v197
	v_fmamk_f32 v211, v77, 0x3dd53b94, v197
	v_fmamk_f32 v212, v78, 0x3dd53b94, v197
	v_fmac_f32_e32 v197, 0x3dd53b94, v79
	v_mfma_f32_32x32x16_bf16 v[64:79], v[226:229], v[134:137], 0
	ds_read_b128 v[222:225], v231 offset:16384
	ds_read_b128 v[226:229], v231 offset:24576
	v_exp_f32_e32 v161, v161
	v_exp_f32_e32 v194, v194
	v_exp_f32_e32 v196, v196
	s_waitcnt lgkmcnt(2)
	v_mfma_f32_32x32x16_bf16 v[64:79], v[218:221], v[130:133], v[64:79]
	ds_read_b128 v[214:217], v234 offset:16384
	ds_read_b128 v[218:221], v234 offset:24576
	v_exp_f32_e32 v192, v192
	v_exp_f32_e32 v195, v195
	v_exp_f32_e32 v187, v187
	s_waitcnt lgkmcnt(3)
	v_mfma_f32_32x32x16_bf16 v[80:95], v[222:225], v[126:129], v[80:95]
	v_exp_f32_e32 v193, v193
	v_exp_f32_e32 v169, v169
	v_exp_f32_e32 v190, v190
	s_waitcnt lgkmcnt(2)
	v_mfma_f32_32x32x16_bf16 v[64:79], v[226:229], v[126:129], v[64:79]
	ds_read_b128 v[222:225], v213 offset:16512
	ds_read_b128 v[226:229], v213 offset:24704
	v_add_u32_e32 v213, s6, v182
	v_exp_f32_e32 v166, v166
	v_exp_f32_e32 v168, v168
	v_exp_f32_e32 v164, v164
	s_waitcnt lgkmcnt(3)
	v_mfma_f32_32x32x16_bf16 v[80:95], v[214:217], v[114:117], v[80:95]
	v_exp_f32_e32 v167, v167
	v_exp_f32_e32 v162, v162
	v_exp_f32_e32 v165, v165
	s_waitcnt lgkmcnt(2)
	v_mfma_f32_32x32x16_bf16 v[64:79], v[218:221], v[114:117], v[64:79]
	ds_read_b128 v[214:217], v230 offset:16512
	ds_read_b128 v[218:221], v230 offset:24704
	v_exp_f32_e32 v163, v163
	v_exp_f32_e32 v198, v198
	v_exp_f32_e32 v199, v199
	s_waitcnt lgkmcnt(3)
	v_mfma_f32_32x32x16_bf16 v[80:95], v[222:225], v[110:113], v[80:95]
	v_exp_f32_e32 v200, v200
	v_exp_f32_e32 v201, v201
	v_exp_f32_e32 v202, v202
	s_waitcnt lgkmcnt(2)
	v_mfma_f32_32x32x16_bf16 v[64:79], v[226:229], v[110:113], v[64:79]
	ds_read_b128 v[222:225], v231 offset:16512
	ds_read_b128 v[226:229], v231 offset:24704
	v_exp_f32_e32 v203, v203
	v_exp_f32_e32 v204, v204
	v_exp_f32_e32 v205, v205
	s_waitcnt lgkmcnt(3)
	v_mfma_f32_32x32x16_bf16 v[80:95], v[214:217], v[106:109], v[80:95]
	v_exp_f32_e32 v206, v206
	v_exp_f32_e32 v207, v207
	v_exp_f32_e32 v210, v210
	s_waitcnt lgkmcnt(2)
; #define QK_FENCE() __builtin_amdgcn_sched_barrier(0x406)
; DI void finishSM(f32x16& p0, f32x16& p1, float alpha, float& l_reg, bf16x8& pa0, bf16x8& pa1, bf16x8& pa2, bf16x8& pa3) {
; #pragma unroll
;   for (int r = 0; r < 16; ++r) p1[r] = __builtin_amdgcn_exp2f(p1[r]);
;   float ps = 0;
; #pragma unroll
;   for (int r = 0; r < 16; ++r) ps += p0[r];
; #pragma unroll
;   for (int r = 0; r < 16; ++r) ps += p1[r];
;   { auto rr = __builtin_amdgcn_permlane32_swap(__float_as_uint(ps), __float_as_uint(ps), false, false);
;     ps = __uint_as_float(rr[0]) + __uint_as_float(rr[1]); }
;   l_reg = l_reg * alpha + ps;
;     ...
;   PK4(p0, 0, pa0); PK4(p0, 8, pa1); PK4(p1, 0, pa2); PK4(p1, 8, pa3);
; DI void qkt12(f32x16& p0, f32x16& p1, const char* Kt, const char* Rt, const int* ko, const int* ro, const bf16x8* qr) {
;   { const f32x16 z = {0.f, 0.f, 0.f, 0.f, 0.f, 0.f, 0.f, 0.f, 0.f, 0.f, 0.f, 0.f, 0.f, 0.f, 0.f, 0.f}; p0 = z; p1 = z; }
;   const char* kp[4] = {Kt + ko[0], Kt + ko[1], Kt + ko[2], Kt + ko[3]};
;   const char* rp[4] = {Rt + ro[0], Rt + ro[1], Rt + ro[2], Rt + ro[3]};
;   bf16x8 ka[2], kb[2];
;   ka[0] = *reinterpret_cast<const bf16x8*>(kp[0]); kb[0] = *reinterpret_cast<const bf16x8*>(kp[0] + 8192);
; #pragma unroll
;   for (int d0 = 0; d0 < 12; ++d0) {
;     if (d0 + 1 < 12) { const int d1 = d0 + 1;
;       if (d1 < 8) { ka[d1 & 1] = *reinterpret_cast<const bf16x8*>(kp[d1 & 3] + (d1 >> 2) * 128); kb[d1 & 1] = *reinterpret_cast<const bf16x8*>(kp[d1 & 3] + (d1 >> 2) * 128 + 8192); }
;       else { ka[d1 & 1] = *reinterpret_cast<const bf16x8*>(rp[d1 - 8]); kb[d1 & 1] = *reinterpret_cast<const bf16x8*>(rp[d1 - 8] + 4096); } }
;     QK_FENCE();
;     p0 = __builtin_amdgcn_mfma_f32_32x32x16_bf16(ka[d0 & 1], qr[d0], p0, 0, 0, 0);
;     p1 = __builtin_amdgcn_mfma_f32_32x32x16_bf16(kb[d0 & 1], qr[d0], p1, 0, 0, 0);
;     QK_FENCE();
;   }
	v_mfma_f32_32x32x16_bf16 v[64:79], v[218:221], v[106:109], v[64:79]
	ds_read_b128 v[214:217], v234 offset:16512
	ds_read_b128 v[218:221], v234 offset:24704
	v_exp_f32_e32 v211, v211
	v_exp_f32_e32 v212, v212
	v_exp_f32_e32 v235, v208
	s_waitcnt lgkmcnt(3)
	v_mfma_f32_32x32x16_bf16 v[80:95], v[222:225], v[102:105], v[80:95]
	v_exp_f32_e32 v237, v197
	v_add_f32_e32 v197, 0, v194
	v_add_f32_e32 v197, v196, v197
	v_add_f32_e32 v197, v192, v197
	v_add_f32_e32 v197, v195, v197
	v_add_f32_e32 v197, v187, v197
	s_waitcnt lgkmcnt(2)
	v_mfma_f32_32x32x16_bf16 v[64:79], v[226:229], v[102:105], v[64:79]
	ds_read_b128 v[222:225], v213 offset:32768
	ds_read_b128 v[226:229], v213 offset:36864
	v_add_u32_e32 v213, s6, v183
	v_add_f32_e32 v197, v193, v197
	v_add_f32_e32 v197, v169, v197
	v_add_f32_e32 v197, v190, v197
	v_add_f32_e32 v197, v166, v197
	v_add_f32_e32 v197, v168, v197
	v_add_f32_e32 v197, v164, v197
	s_waitcnt lgkmcnt(3)
	v_mfma_f32_32x32x16_bf16 v[80:95], v[214:217], v[98:101], v[80:95]
	v_add_f32_e32 v197, v167, v197
	v_add_f32_e32 v197, v162, v197
	v_add_f32_e32 v197, v165, v197
	v_add_f32_e32 v197, v161, v197
	v_add_f32_e32 v197, v163, v197
	v_add_f32_e32 v197, v198, v197
	v_add_f32_e32 v197, v199, v197
	s_waitcnt lgkmcnt(2)
	v_mfma_f32_32x32x16_bf16 v[64:79], v[218:221], v[98:101], v[64:79]
	ds_read_b128 v[214:217], v213 offset:32768
	ds_read_b128 v[218:221], v213 offset:36864
	v_add_u32_e32 v213, s6, v184
	v_add_f32_e32 v197, v200, v197
	v_add_f32_e32 v197, v201, v197
	v_add_f32_e32 v197, v202, v197
	v_add_f32_e32 v197, v203, v197
	v_add_f32_e32 v197, v204, v197
	s_waitcnt lgkmcnt(3)
	v_mfma_f32_32x32x16_bf16 v[80:95], v[222:225], v[122:125], v[80:95]
	v_exp_f32_e32 v241, v209
	v_add_f32_e32 v197, v205, v197
	v_add_f32_e32 v197, v206, v197
	v_add_f32_e32 v197, v207, v197
	v_add_f32_e32 v197, v235, v197
	v_add_f32_e32 v197, v241, v197
	s_waitcnt lgkmcnt(2)
	v_mfma_f32_32x32x16_bf16 v[64:79], v[226:229], v[122:125], v[64:79]
	ds_read_b128 v[222:225], v213 offset:32768
	ds_read_b128 v[226:229], v213 offset:36864
	v_add_u32_e32 v213, s6, v185
	v_add_f32_e32 v197, v210, v197
	v_add_f32_e32 v197, v211, v197
	v_add_f32_e32 v197, v212, v197
	v_add_f32_e32 v208, v237, v197
	v_mov_b32_e32 v209, v208
	v_cvt_pk_bf16_f32 v194, v194, v196
	s_waitcnt lgkmcnt(3)
	v_mfma_f32_32x32x16_bf16 v[80:95], v[214:217], v[142:145], v[80:95]
	v_permlane32_swap_b32_e32 v208, v209
	v_cvt_pk_bf16_f32 v195, v192, v195
	v_cvt_pk_bf16_f32 v196, v187, v193
	v_cvt_pk_bf16_f32 v197, v169, v190
	v_cvt_pk_bf16_f32 v166, v166, v168
	v_cvt_pk_bf16_f32 v167, v164, v167
	v_cvt_pk_bf16_f32 v168, v162, v165
	s_waitcnt lgkmcnt(2)
	v_mfma_f32_32x32x16_bf16 v[64:79], v[218:221], v[142:145], v[64:79]
	ds_read_b128 v[214:217], v213 offset:32768
	ds_read_b128 v[218:221], v213 offset:36864
	v_cvt_pk_bf16_f32 v169, v161, v163
	v_cvt_pk_bf16_f32 v162, v198, v199
	v_cvt_pk_bf16_f32 v163, v200, v201
	v_cvt_pk_bf16_f32 v164, v202, v203
	v_cvt_pk_bf16_f32 v165, v204, v205
	v_cvt_pk_bf16_f32 v198, v206, v207
	v_cvt_pk_bf16_f32 v199, v235, v241
	s_waitcnt lgkmcnt(3)
	v_mfma_f32_32x32x16_bf16 v[80:95], v[222:225], v[118:121], v[80:95]
	v_cvt_pk_bf16_f32 v200, v210, v211
	v_cvt_pk_bf16_f32 v201, v212, v237
	v_permlane32_swap_b32_e32 v194, v196
	v_permlane32_swap_b32_e32 v195, v197
	v_permlane32_swap_b32_e32 v166, v168
	v_permlane32_swap_b32_e32 v167, v169
	v_permlane32_swap_b32_e32 v162, v164
	s_waitcnt lgkmcnt(2)
	v_mfma_f32_32x32x16_bf16 v[64:79], v[226:229], v[118:121], v[64:79]
	v_permlane32_swap_b32_e32 v163, v165
	v_permlane32_swap_b32_e32 v198, v200
	v_permlane32_swap_b32_e32 v199, v201
	s_waitcnt lgkmcnt(1)
	v_mfma_f32_32x32x16_bf16 v[80:95], v[214:217], v[138:141], v[80:95]
	s_waitcnt lgkmcnt(0)
; #define SBAR() __builtin_amdgcn_sched_barrier(0)
; template <int OFF> DI s16x4 tr_read(int vb) { s16x4 r; asm volatile("ds_read_b64_tr_b16 %0, %1 offset:%2" : "=&v"(r) : "v"(vb), "i"(OFF) : "memory"); return r; }
; DI void partialSM(f32x16& p0, f32x16& p1, float& m_reg, float& mn, float& alpha) {
;   constexpr float C = ATT_SCALE * 1.4426950408889634f;
;   float pmax = p0[0];
; #pragma unroll
;   for (int r = 1; r < 16; ++r) pmax = fmaxf(pmax, p0[r]);
; #pragma unroll
;   for (int r = 0; r < 16; ++r) pmax = fmaxf(pmax, p1[r]);
;   { auto rr = __builtin_amdgcn_permlane32_swap(__float_as_uint(pmax), __float_as_uint(pmax), false, false);
;     pmax = fmaxf(__uint_as_float(rr[0]), __uint_as_float(rr[1])); }
;   if (__builtin_expect(__all(pmax - m_reg <= ATT_THR / ATT_SCALE), 1)) { mn = m_reg; alpha = 1.f; }
; template <int D0> DI void pv_one(f32x16& od, int vb, bf16x8 pa0, bf16x8 pa1, bf16x8 pa2, bf16x8 pa3) {
;   const s16x4 l0 = tr_read<v_rd_off(D0, 0, 0)>(vb), h0 = tr_read<v_rd_off(D0, 0, 1)>(vb), l1 = tr_read<v_rd_off(D0, 1, 0)>(vb), h1 = tr_read<v_rd_off(D0, 1, 1)>(vb);
;   const s16x4 l2 = tr_read<v_rd_off(D0, 2, 0)>(vb), h2 = tr_read<v_rd_off(D0, 2, 1)>(vb), l3 = tr_read<v_rd_off(D0, 3, 0)>(vb), h3 = tr_read<v_rd_off(D0, 3, 1)>(vb);
;   asm volatile("s_waitcnt lgkmcnt(0)" ::: "memory"); SBAR();
;     ...
;   od = __builtin_amdgcn_mfma_f32_32x32x16_bf16(pa0, PK(l0, h0), od, 0, 0, 0);
;   od = __builtin_amdgcn_mfma_f32_32x32x16_bf16(pa1, PK(l1, h1), od, 0, 0, 0);
;   od = __builtin_amdgcn_mfma_f32_32x32x16_bf16(pa2, PK(l2, h2), od, 0, 0, 0);
;   od = __builtin_amdgcn_mfma_f32_32x32x16_bf16(pa3, PK(l3, h3), od, 0, 0, 0);
;     ...
; }
; DI void pv_d0(f32x16* o, int vb, bf16x8 pa0, bf16x8 pa1, bf16x8 pa2, bf16x8 pa3) {
;   pv_one<0>(o[0], vb, pa0, pa1, pa2, pa3); pv_one<1>(o[1], vb, pa0, pa1, pa2, pa3); pv_one<2>(o[2], vb, pa0, pa1, pa2, pa3); pv_one<3>(o[3], vb, pa0, pa1, pa2, pa3);
	v_mfma_f32_32x32x16_bf16 v[64:79], v[218:221], v[138:141], v[64:79]
	v_add_u32_e32 v161, s42, v174
	ds_read_b64_tr_b16 v[202:203], v161 offset:0
	ds_read_b64_tr_b16 v[204:205], v161 offset:0x800
	ds_read_b64_tr_b16 v[210:211], v161 offset:0x1000
	ds_read_b64_tr_b16 v[212:213], v161 offset:0x1800
	ds_read_b64_tr_b16 v[214:215], v161 offset:0x2000
	ds_read_b64_tr_b16 v[216:217], v161 offset:0x2800
	ds_read_b64_tr_b16 v[218:219], v161 offset:0x3000
	ds_read_b64_tr_b16 v[220:221], v161 offset:0x3800
	s_waitcnt lgkmcnt(6)
	v_max_f32_e32 v235, v81, v81
	v_max_f32_e32 v237, v80, v80
	v_max_f32_e32 v235, v237, v235
	v_max3_f32 v235, v235, v82, v83
	v_max3_f32 v235, v235, v84, v85
	v_max3_f32 v235, v235, v86, v87
	v_mfma_f32_32x32x16_bf16 v[0:15], v[194:197], v[202:205], v[0:15]
	ds_read_b64_tr_b16 v[202:203], v161 offset:0x200
	ds_read_b64_tr_b16 v[204:205], v161 offset:0xa00
	v_max3_f32 v235, v235, v88, v89
	v_max3_f32 v235, v235, v90, v91
	v_max3_f32 v235, v235, v92, v93
	v_max3_f32 v235, v235, v94, v95
	v_max3_f32 v235, v235, v64, v65
	v_max3_f32 v235, v235, v66, v67
	v_max3_f32 v235, v235, v68, v69
	s_waitcnt lgkmcnt(6)
	v_mfma_f32_32x32x16_bf16 v[0:15], v[166:169], v[210:213], v[0:15]
	ds_read_b64_tr_b16 v[210:211], v161 offset:0x1200
	ds_read_b64_tr_b16 v[212:213], v161 offset:0x1a00
	v_max3_f32 v235, v235, v70, v71
	v_max3_f32 v235, v235, v72, v73
	v_max3_f32 v235, v235, v74, v75
	v_max3_f32 v235, v235, v76, v77
	v_max3_f32 v235, v235, v78, v79
	v_mov_b32_e32 v237, v235
	s_waitcnt lgkmcnt(6)
	v_mfma_f32_32x32x16_bf16 v[0:15], v[162:165], v[214:217], v[0:15]
	ds_read_b64_tr_b16 v[214:215], v161 offset:0x2200
	ds_read_b64_tr_b16 v[216:217], v161 offset:0x2a00
	v_permlane32_swap_b32_e32 v235, v237
	v_max_f32_e32 v237, v237, v237
	v_max_f32_e32 v235, v235, v235
	s_waitcnt lgkmcnt(6)
	v_mfma_f32_32x32x16_bf16 v[0:15], v[198:201], v[218:221], v[0:15]
	ds_read_b64_tr_b16 v[218:219], v161 offset:0x3200
	ds_read_b64_tr_b16 v[220:221], v161 offset:0x3a00
	s_waitcnt lgkmcnt(6)
	v_mfma_f32_32x32x16_bf16 v[48:63], v[194:197], v[202:205], v[48:63]
	ds_read_b64_tr_b16 v[202:203], v161 offset:0x400
	ds_read_b64_tr_b16 v[204:205], v161 offset:0xc00
	s_waitcnt lgkmcnt(6)
	v_mfma_f32_32x32x16_bf16 v[48:63], v[166:169], v[210:213], v[48:63]
	ds_read_b64_tr_b16 v[210:211], v161 offset:0x1400
	ds_read_b64_tr_b16 v[212:213], v161 offset:0x1c00
	s_waitcnt lgkmcnt(6)
	v_mfma_f32_32x32x16_bf16 v[48:63], v[162:165], v[214:217], v[48:63]
	ds_read_b64_tr_b16 v[214:215], v161 offset:0x2400
	ds_read_b64_tr_b16 v[216:217], v161 offset:0x2c00
	s_waitcnt lgkmcnt(6)
	v_mfma_f32_32x32x16_bf16 v[48:63], v[198:201], v[218:221], v[48:63]
	ds_read_b64_tr_b16 v[218:219], v161 offset:0x3400
	ds_read_b64_tr_b16 v[220:221], v161 offset:0x3c00
	s_waitcnt lgkmcnt(6)
	v_mfma_f32_32x32x16_bf16 v[32:47], v[194:197], v[202:205], v[32:47]
	ds_read_b64_tr_b16 v[202:203], v161 offset:0x600
	ds_read_b64_tr_b16 v[204:205], v161 offset:0xe00
	s_waitcnt lgkmcnt(6)
	v_mfma_f32_32x32x16_bf16 v[32:47], v[166:169], v[210:213], v[32:47]
	ds_read_b64_tr_b16 v[210:211], v161 offset:0x1600
	ds_read_b64_tr_b16 v[212:213], v161 offset:0x1e00
	s_waitcnt lgkmcnt(6)
	v_mfma_f32_32x32x16_bf16 v[32:47], v[162:165], v[214:217], v[32:47]
	ds_read_b64_tr_b16 v[214:215], v161 offset:0x2600
	ds_read_b64_tr_b16 v[216:217], v161 offset:0x2e00
	s_waitcnt lgkmcnt(6)
	v_mfma_f32_32x32x16_bf16 v[32:47], v[198:201], v[218:221], v[32:47]
	ds_read_b64_tr_b16 v[218:219], v161 offset:0x3600
	ds_read_b64_tr_b16 v[220:221], v161 offset:0x3e00
	v_max_f32_e32 v161, v235, v237
	v_sub_f32_e32 v237, v161, v160
	s_waitcnt lgkmcnt(6)
	v_mfma_f32_32x32x16_bf16 v[16:31], v[194:197], v[202:205], v[16:31]
	s_waitcnt lgkmcnt(4)
	v_mfma_f32_32x32x16_bf16 v[16:31], v[166:169], v[210:213], v[16:31]
	s_waitcnt lgkmcnt(2)
	v_mfma_f32_32x32x16_bf16 v[16:31], v[162:165], v[214:217], v[16:31]
	s_waitcnt lgkmcnt(0)
	v_mfma_f32_32x32x16_bf16 v[16:31], v[198:201], v[218:221], v[16:31]
	v_cmp_ge_f32_e32 vcc, s65, v237
	s_cmp_eq_u64 vcc, exec
	s_cselect_b64 s[38:39], -1, 0
	s_cmp_ge_u32 s12, s52
	s_cselect_b64 s[42:43], -1, 0
	s_and_b64 vcc, exec, s[42:43]
	s_waitcnt vmcnt(0)
	s_waitcnt vmcnt(0)
	s_barrier

; #define SBAR() __builtin_amdgcn_sched_barrier(0)
; #define RESC(a) do { if (__any((a) < 1.f)) { if (hi == 0) al_l[r32] = (a); asm volatile("s_waitcnt lgkmcnt(0)" ::: "memory"); \
;     _Pragma("unroll") for (int d = 0; d < 4; ++d) _Pragma("unroll") for (int r = 0; r < 16; ++r) o[d][r] *= al_l[crow(r, hi)]; } } while (0)
; #define VWAIT() asm volatile("s_waitcnt vmcnt(0)" ::: "memory")
; #define RESC(a) do { if (__any((a) < 1.f)) { if (hi == 0) al_l[r32] = (a); asm volatile("s_waitcnt lgkmcnt(0)" ::: "memory"); \
;     _Pragma("unroll") for (int d = 0; d < 4; ++d) _Pragma("unroll") for (int r = 0; r < 16; ++r) o[d][r] *= al_l[crow(r, hi)]; } } while (0)
; DI void partialSM(f32x16& p0, f32x16& p1, float& m_reg, float& mn, float& alpha) {
;     ...
;   if (__builtin_expect(__all(pmax - m_reg <= ATT_THR / ATT_SCALE), 1)) { mn = m_reg; alpha = 1.f; }
;   else { mn = fmaxf(m_reg, pmax); alpha = __builtin_amdgcn_exp2f((m_reg - mn) * C); m_reg = mn; }
;   const float mnC = -mn * C;
; #pragma unroll
;   for (int r = 0; r < 16; ++r) p0[r] = fmaf(p0[r], C, mnC);
; #pragma unroll
;   for (int r = 0; r < 16; ++r) p1[r] = fmaf(p1[r], C, mnC);
; DI void attn_item_dma(const u16* Qb, const u16* Kh, const u16* Vh, const u16* Rh, u16* Ob, int seq, const float* rope, int pos0, char* lds) {
;     ...
;   for (int j = 1; j + 1 < NT; j += 2) {
;     const int sp = PRV(sj), sn = NXT(sj);
;     SBAR(); qkt12(pB0, pB1, lds + sj * STG + 16384, lds + sj * STG + 32768, ko, ro, qr);
;     finishSM(pA0, pA1, alA, l_reg, pa0, pa1, pa2, pa3); SBAR();
;     pv_d0(o, vb0 + sp * STG, pa0, pa1, pa2, pa3); partialSM(pB0, pB1, m_reg, mnB, alB);
;     VWAIT(); __syncthreads();
;     if (j + 2 < NT) DMA(j + 2, sp);
;     RESC(alB);
;     SBAR(); qkt12(pA0, pA1, lds + sn * STG + 16384, lds + sn * STG + 32768, ko, ro, qr);
;     finishSM(pB0, pB1, alB, l_reg, pa0, pa1, pa2, pa3); SBAR();
;     pv_d0(o, vb0 + sj * STG, pa0, pa1, pa2, pa3); partialSM(pA0, pA1, m_reg, mnA, alA);
;     VWAIT(); __syncthreads();
;     if (j + 3 < NT) DMA(j + 3, sj);
;     RESC(alA);
;     sj = PRV(sj);
;   }
.LBB0_134:
	v_cndmask_b32_e64 v187, v154, v160, s[38:39]
	v_mul_f32_e32 v158, 0xbdd53b94, v187
	v_mov_b32_e32 v159, v158
	v_fmamk_f32 v200, v80, 0x3dd53b94, v158
	v_fmamk_f32 v202, v81, 0x3dd53b94, v158
	v_fmamk_f32 v201, v82, 0x3dd53b94, v158
	v_fmamk_f32 v204, v83, 0x3dd53b94, v158
	v_fmamk_f32 v203, v84, 0x3dd53b94, v158
	v_fmamk_f32 v206, v85, 0x3dd53b94, v158
	v_fmamk_f32 v205, v86, 0x3dd53b94, v158
	v_fmamk_f32 v207, v87, 0x3dd53b94, v158
	v_fmamk_f32 v192, v88, 0x3dd53b94, v158
	v_fmamk_f32 v194, v89, 0x3dd53b94, v158
	v_fmamk_f32 v193, v90, 0x3dd53b94, v158
	v_fmamk_f32 v196, v91, 0x3dd53b94, v158
	v_fmamk_f32 v195, v92, 0x3dd53b94, v158
	v_fmamk_f32 v198, v93, 0x3dd53b94, v158
	v_fmamk_f32 v197, v94, 0x3dd53b94, v158
	v_fmamk_f32 v199, v95, 0x3dd53b94, v159
	v_fmamk_f32 v167, v65, 0x3dd53b94, v158
	v_fmamk_f32 v166, v64, 0x3dd53b94, v158
	v_add_f32_e32 v64, v188, v189
	v_fmac_f32_e32 v64, v186, v173
	v_add_f32_e32 v173, v208, v209
	v_fmamk_f32 v163, v67, 0x3dd53b94, v158
	v_fmamk_f32 v162, v66, 0x3dd53b94, v158
	v_fmamk_f32 v161, v69, 0x3dd53b94, v158
	v_fmamk_f32 v160, v68, 0x3dd53b94, v158
	v_fmamk_f32 v157, v71, 0x3dd53b94, v158
	v_fmamk_f32 v156, v70, 0x3dd53b94, v158
	v_fmamk_f32 v155, v73, 0x3dd53b94, v158
	v_fmamk_f32 v154, v72, 0x3dd53b94, v158
	v_fmamk_f32 v169, v75, 0x3dd53b94, v158
	v_fmamk_f32 v168, v74, 0x3dd53b94, v158
	v_fmamk_f32 v165, v77, 0x3dd53b94, v158
	v_fmamk_f32 v164, v76, 0x3dd53b94, v158
	v_fmamk_f32 v159, v79, 0x3dd53b94, v158
	v_fmamk_f32 v158, v78, 0x3dd53b94, v158
	v_fmac_f32_e32 v173, v64, v191
	v_lshl_add_u64 v[148:149], v[148:149], 0, s[68:69]
	v_lshl_add_u64 v[150:151], v[150:151], 0, s[66:67]
	v_lshl_add_u64 v[152:153], v[152:153], 0, s[66:67]
	s_add_i32 s12, s12, 2
	s_and_b64 vcc, exec, s[42:43]
	s_cbranch_vccnz .LBB0_136
	s_mov_b32 s61, s13
	v_mov_b32_e32 v186, v190
	s_branch .LBB0_122
